# gate_up SwiGLU epilogue regenerated 8-wide (all 8 outputs per stage: exp/add/rcp chains independent, packed broadcast scaling, f32 throughout), placement of later code kept fixed
# baseline (speedup 1.0000x reference)
; __device__ __forceinline__ unsigned cvtpk(float lo, float hi) { f32x2 v = {lo, hi}; bf16x2_t b = __builtin_convertvector(v, bf16x2_t); return __builtin_bit_cast(unsigned, b); }
;     __device__ __forceinline__ void operator()(const f32x4 (&acc)[2][2][4][2], const Unit& u, int wr, int wc, int fr, int fq, const float (&pv)[8]) const {
;     ...
;             for (int m = 0; m < 4; ++m) { const int row = row0 + ai * HALF + m * 16; const float rs = __builtin_amdgcn_rsqf(pv[ai * 4 + m] * (1.f / DM) + EPS);
;                 float hv[8];
; #pragma unroll
;                 for (int n = 0; n < 2; ++n)
; #pragma unroll
;                     for (int j = 0; j < 4; ++j) { const float g = acc[ai][0][m][n][j] * rs, uu = acc[ai][1][m][n][j] * rs;
;                         const float e = __builtin_amdgcn_exp2f(-g * LOG2E); hv[n * 4 + j] = g * uu * __builtin_amdgcn_rcpf(1.f + e); }
;                 u32x4 w; w.x = cvtpk(hv[0], hv[1]); w.y = cvtpk(hv[2], hv[3]); w.z = cvtpk(hv[4], hv[5]); w.w = cvtpk(hv[6], hv[7]);
;                 *(u32x4*)(H + (size_t)row * DFF + col0) = w; }
.LBB0_151:
	s_waitcnt vmcnt(8)
	v_lshl_or_b32 v156, s18, 7, v146
	v_ashrrev_i32_e32 v157, 31, v156
	s_movk_i32 s10, 0x1600
	v_lshlrev_b64 v[224:225], 1, v[156:157]
	v_lshl_add_u64 v[224:225], v[224:225], 0, s[14:15]
	v_fmamk_f32 v141, v148, 0x3a800000, v222
	v_rsq_f32_e32 v220, v141
	v_mad_i64_i32 v[162:163], vcc, v140, s10, v[224:225]
	v_pk_mul_f32 v[118:119], v[126:127], v[118:119]
	v_pk_mul_f32 v[120:121], v[128:129], v[120:121]
	v_pk_mul_f32 v[114:115], v[122:123], v[114:115]
	v_pk_mul_f32 v[116:117], v[124:125], v[116:117]
	v_mul_f32_e32 v142, 0xbfb8aa3b, v220
	v_mul_f32_e32 v220, v220, v220
	v_pk_mul_f32 v[250:251], v[142:143], v[126:127] op_sel_hi:[0,1]
	v_pk_mul_f32 v[252:253], v[142:143], v[128:129] op_sel_hi:[0,1]
	v_pk_mul_f32 v[230:231], v[142:143], v[122:123] op_sel_hi:[0,1]
	v_pk_mul_f32 v[232:233], v[142:143], v[124:125] op_sel_hi:[0,1]
	v_exp_f32_e32 v250, v250
	v_exp_f32_e32 v251, v251
	v_exp_f32_e32 v252, v252
	v_exp_f32_e32 v253, v253
	v_exp_f32_e32 v230, v230
	v_exp_f32_e32 v231, v231
	v_exp_f32_e32 v232, v232
	v_exp_f32_e32 v233, v233
	v_add_f32_e32 v250, 1.0, v250
	v_add_f32_e32 v251, 1.0, v251
	v_add_f32_e32 v252, 1.0, v252
	v_add_f32_e32 v253, 1.0, v253
	v_add_f32_e32 v230, 1.0, v230
	v_add_f32_e32 v231, 1.0, v231
	v_add_f32_e32 v232, 1.0, v232
	v_add_f32_e32 v233, 1.0, v233
	v_rcp_f32_e32 v250, v250
	v_rcp_f32_e32 v251, v251
	v_rcp_f32_e32 v252, v252
	v_rcp_f32_e32 v253, v253
	v_rcp_f32_e32 v230, v230
	v_rcp_f32_e32 v231, v231
	v_rcp_f32_e32 v232, v232
	v_rcp_f32_e32 v233, v233
	v_pk_mul_f32 v[118:119], v[220:221], v[118:119] op_sel_hi:[0,1]
	v_pk_mul_f32 v[120:121], v[220:221], v[120:121] op_sel_hi:[0,1]
	v_pk_mul_f32 v[114:115], v[220:221], v[114:115] op_sel_hi:[0,1]
	v_pk_mul_f32 v[116:117], v[220:221], v[116:117] op_sel_hi:[0,1]
	v_pk_mul_f32 v[118:119], v[250:251], v[118:119]
	v_pk_mul_f32 v[120:121], v[252:253], v[120:121]
	v_pk_mul_f32 v[114:115], v[230:231], v[114:115]
	v_pk_mul_f32 v[116:117], v[232:233], v[116:117]
	v_cvt_pk_bf16_f32 v126, v118, v119
	v_cvt_pk_bf16_f32 v127, v120, v121
	v_cvt_pk_bf16_f32 v128, v114, v115
	v_cvt_pk_bf16_f32 v129, v116, v117
	global_store_dwordx4 v[162:163], v[126:129], off
	v_fmamk_f32 v141, v149, 0x3a800000, v222
	v_rsq_f32_e32 v220, v141
	v_add_u32_e32 v184, 0x10, v140
	v_mad_i64_i32 v[162:163], vcc, v184, s10, v[224:225]
	v_pk_mul_f32 v[102:103], v[110:111], v[102:103]
	v_pk_mul_f32 v[104:105], v[112:113], v[104:105]
	v_pk_mul_f32 v[98:99], v[106:107], v[98:99]
	v_pk_mul_f32 v[100:101], v[108:109], v[100:101]
	v_mul_f32_e32 v142, 0xbfb8aa3b, v220
	v_mul_f32_e32 v220, v220, v220
	v_pk_mul_f32 v[250:251], v[142:143], v[110:111] op_sel_hi:[0,1]
	v_pk_mul_f32 v[252:253], v[142:143], v[112:113] op_sel_hi:[0,1]
	v_pk_mul_f32 v[230:231], v[142:143], v[106:107] op_sel_hi:[0,1]
	v_pk_mul_f32 v[232:233], v[142:143], v[108:109] op_sel_hi:[0,1]
	v_exp_f32_e32 v250, v250
	v_exp_f32_e32 v251, v251
	v_exp_f32_e32 v252, v252
	v_exp_f32_e32 v253, v253
	v_exp_f32_e32 v230, v230
	v_exp_f32_e32 v231, v231
	v_exp_f32_e32 v232, v232
	v_exp_f32_e32 v233, v233
	v_add_f32_e32 v250, 1.0, v250
	v_add_f32_e32 v251, 1.0, v251
	v_add_f32_e32 v252, 1.0, v252
	v_add_f32_e32 v253, 1.0, v253
	v_add_f32_e32 v230, 1.0, v230
	v_add_f32_e32 v231, 1.0, v231
	v_add_f32_e32 v232, 1.0, v232
	v_add_f32_e32 v233, 1.0, v233
	v_rcp_f32_e32 v250, v250
	v_rcp_f32_e32 v251, v251
	v_rcp_f32_e32 v252, v252
	v_rcp_f32_e32 v253, v253
	v_rcp_f32_e32 v230, v230
	v_rcp_f32_e32 v231, v231
	v_rcp_f32_e32 v232, v232
	v_rcp_f32_e32 v233, v233
	v_pk_mul_f32 v[102:103], v[220:221], v[102:103] op_sel_hi:[0,1]
	v_pk_mul_f32 v[104:105], v[220:221], v[104:105] op_sel_hi:[0,1]
	v_pk_mul_f32 v[98:99], v[220:221], v[98:99] op_sel_hi:[0,1]
	v_pk_mul_f32 v[100:101], v[220:221], v[100:101] op_sel_hi:[0,1]
	v_pk_mul_f32 v[102:103], v[250:251], v[102:103]
	v_pk_mul_f32 v[104:105], v[252:253], v[104:105]
	v_pk_mul_f32 v[98:99], v[230:231], v[98:99]
	v_pk_mul_f32 v[100:101], v[232:233], v[100:101]
	v_cvt_pk_bf16_f32 v110, v102, v103
	v_cvt_pk_bf16_f32 v111, v104, v105
	v_cvt_pk_bf16_f32 v112, v98, v99
	v_cvt_pk_bf16_f32 v113, v100, v101
	global_store_dwordx4 v[162:163], v[110:113], off
	v_fmamk_f32 v141, v150, 0x3a800000, v222
	v_rsq_f32_e32 v220, v141
	v_add_u32_e32 v184, 0x20, v140
	v_mad_i64_i32 v[162:163], vcc, v184, s10, v[224:225]
	v_pk_mul_f32 v[86:87], v[94:95], v[86:87]
	v_pk_mul_f32 v[88:89], v[96:97], v[88:89]
	v_pk_mul_f32 v[82:83], v[90:91], v[82:83]
	v_pk_mul_f32 v[84:85], v[92:93], v[84:85]
	v_mul_f32_e32 v142, 0xbfb8aa3b, v220
	v_mul_f32_e32 v220, v220, v220
	v_pk_mul_f32 v[250:251], v[142:143], v[94:95] op_sel_hi:[0,1]
	v_pk_mul_f32 v[252:253], v[142:143], v[96:97] op_sel_hi:[0,1]
	v_pk_mul_f32 v[230:231], v[142:143], v[90:91] op_sel_hi:[0,1]
	v_pk_mul_f32 v[232:233], v[142:143], v[92:93] op_sel_hi:[0,1]
	v_exp_f32_e32 v250, v250
	v_exp_f32_e32 v251, v251
	v_exp_f32_e32 v252, v252
	v_exp_f32_e32 v253, v253
	v_exp_f32_e32 v230, v230
	v_exp_f32_e32 v231, v231
	v_exp_f32_e32 v232, v232
	v_exp_f32_e32 v233, v233
	v_add_f32_e32 v250, 1.0, v250
	v_add_f32_e32 v251, 1.0, v251
	v_add_f32_e32 v252, 1.0, v252
	v_add_f32_e32 v253, 1.0, v253
	v_add_f32_e32 v230, 1.0, v230
	v_add_f32_e32 v231, 1.0, v231
	v_add_f32_e32 v232, 1.0, v232
	v_add_f32_e32 v233, 1.0, v233
	v_rcp_f32_e32 v250, v250
	v_rcp_f32_e32 v251, v251
	v_rcp_f32_e32 v252, v252
	v_rcp_f32_e32 v253, v253
	v_rcp_f32_e32 v230, v230
	v_rcp_f32_e32 v231, v231
	v_rcp_f32_e32 v232, v232
	v_rcp_f32_e32 v233, v233
	v_pk_mul_f32 v[86:87], v[220:221], v[86:87] op_sel_hi:[0,1]
	v_pk_mul_f32 v[88:89], v[220:221], v[88:89] op_sel_hi:[0,1]
	v_pk_mul_f32 v[82:83], v[220:221], v[82:83] op_sel_hi:[0,1]
; __device__ __forceinline__ unsigned cvtpk(float lo, float hi) { f32x2 v = {lo, hi}; bf16x2_t b = __builtin_convertvector(v, bf16x2_t); return __builtin_bit_cast(unsigned, b); }
;     __device__ __forceinline__ void operator()(const f32x4 (&acc)[2][2][4][2], const Unit& u, int wr, int wc, int fr, int fq, const float (&pv)[8]) const {
;     ...
;             for (int m = 0; m < 4; ++m) { const int row = row0 + ai * HALF + m * 16; const float rs = __builtin_amdgcn_rsqf(pv[ai * 4 + m] * (1.f / DM) + EPS);
;                 float hv[8];
; #pragma unroll
;                 for (int n = 0; n < 2; ++n)
; #pragma unroll
;                     for (int j = 0; j < 4; ++j) { const float g = acc[ai][0][m][n][j] * rs, uu = acc[ai][1][m][n][j] * rs;
;                         const float e = __builtin_amdgcn_exp2f(-g * LOG2E); hv[n * 4 + j] = g * uu * __builtin_amdgcn_rcpf(1.f + e); }
;                 u32x4 w; w.x = cvtpk(hv[0], hv[1]); w.y = cvtpk(hv[2], hv[3]); w.z = cvtpk(hv[4], hv[5]); w.w = cvtpk(hv[6], hv[7]);
;                 *(u32x4*)(H + (size_t)row * DFF + col0) = w; }
	v_pk_mul_f32 v[84:85], v[220:221], v[84:85] op_sel_hi:[0,1]
	v_pk_mul_f32 v[86:87], v[250:251], v[86:87]
	v_pk_mul_f32 v[88:89], v[252:253], v[88:89]
	v_pk_mul_f32 v[82:83], v[230:231], v[82:83]
	v_pk_mul_f32 v[84:85], v[232:233], v[84:85]
	v_cvt_pk_bf16_f32 v94, v86, v87
	v_cvt_pk_bf16_f32 v95, v88, v89
	v_cvt_pk_bf16_f32 v96, v82, v83
	v_cvt_pk_bf16_f32 v97, v84, v85
	global_store_dwordx4 v[162:163], v[94:97], off
	v_fmamk_f32 v141, v151, 0x3a800000, v222
	v_rsq_f32_e32 v220, v141
	v_add_u32_e32 v184, 0x30, v140
	v_mad_i64_i32 v[162:163], vcc, v184, s10, v[224:225]
	v_pk_mul_f32 v[70:71], v[78:79], v[70:71]
	v_pk_mul_f32 v[72:73], v[80:81], v[72:73]
	v_pk_mul_f32 v[66:67], v[74:75], v[66:67]
	v_pk_mul_f32 v[68:69], v[76:77], v[68:69]
	v_mul_f32_e32 v142, 0xbfb8aa3b, v220
	v_mul_f32_e32 v220, v220, v220
	v_pk_mul_f32 v[250:251], v[142:143], v[78:79] op_sel_hi:[0,1]
	v_pk_mul_f32 v[252:253], v[142:143], v[80:81] op_sel_hi:[0,1]
	v_pk_mul_f32 v[230:231], v[142:143], v[74:75] op_sel_hi:[0,1]
	v_pk_mul_f32 v[232:233], v[142:143], v[76:77] op_sel_hi:[0,1]
	v_exp_f32_e32 v250, v250
	v_exp_f32_e32 v251, v251
	v_exp_f32_e32 v252, v252
	v_exp_f32_e32 v253, v253
	v_exp_f32_e32 v230, v230
	v_exp_f32_e32 v231, v231
	v_exp_f32_e32 v232, v232
	v_exp_f32_e32 v233, v233
	v_add_f32_e32 v250, 1.0, v250
	v_add_f32_e32 v251, 1.0, v251
	v_add_f32_e32 v252, 1.0, v252
	v_add_f32_e32 v253, 1.0, v253
	v_add_f32_e32 v230, 1.0, v230
	v_add_f32_e32 v231, 1.0, v231
	v_add_f32_e32 v232, 1.0, v232
	v_add_f32_e32 v233, 1.0, v233
	v_rcp_f32_e32 v250, v250
	v_rcp_f32_e32 v251, v251
	v_rcp_f32_e32 v252, v252
	v_rcp_f32_e32 v253, v253
	v_rcp_f32_e32 v230, v230
	v_rcp_f32_e32 v231, v231
	v_rcp_f32_e32 v232, v232
	v_rcp_f32_e32 v233, v233
	v_pk_mul_f32 v[70:71], v[220:221], v[70:71] op_sel_hi:[0,1]
	v_pk_mul_f32 v[72:73], v[220:221], v[72:73] op_sel_hi:[0,1]
	v_pk_mul_f32 v[66:67], v[220:221], v[66:67] op_sel_hi:[0,1]
	v_pk_mul_f32 v[68:69], v[220:221], v[68:69] op_sel_hi:[0,1]
	v_pk_mul_f32 v[70:71], v[250:251], v[70:71]
	v_pk_mul_f32 v[72:73], v[252:253], v[72:73]
	v_pk_mul_f32 v[66:67], v[230:231], v[66:67]
	v_pk_mul_f32 v[68:69], v[232:233], v[68:69]
	v_cvt_pk_bf16_f32 v78, v70, v71
	v_cvt_pk_bf16_f32 v79, v72, v73
	v_cvt_pk_bf16_f32 v80, v66, v67
	v_cvt_pk_bf16_f32 v81, v68, v69
	global_store_dwordx4 v[162:163], v[78:81], off
	v_fmamk_f32 v141, v152, 0x3a800000, v222
	v_rsq_f32_e32 v220, v141
	v_add_u32_e32 v184, 0x80, v140
	v_mad_i64_i32 v[162:163], vcc, v184, s10, v[224:225]
	v_pk_mul_f32 v[54:55], v[62:63], v[54:55]
	v_pk_mul_f32 v[56:57], v[64:65], v[56:57]
	v_pk_mul_f32 v[50:51], v[58:59], v[50:51]
	v_pk_mul_f32 v[52:53], v[60:61], v[52:53]
	v_mul_f32_e32 v142, 0xbfb8aa3b, v220
	v_mul_f32_e32 v220, v220, v220
	v_pk_mul_f32 v[250:251], v[142:143], v[62:63] op_sel_hi:[0,1]
	v_pk_mul_f32 v[252:253], v[142:143], v[64:65] op_sel_hi:[0,1]
	v_pk_mul_f32 v[230:231], v[142:143], v[58:59] op_sel_hi:[0,1]
	v_pk_mul_f32 v[232:233], v[142:143], v[60:61] op_sel_hi:[0,1]
	v_exp_f32_e32 v250, v250
	v_exp_f32_e32 v251, v251
	v_exp_f32_e32 v252, v252
	v_exp_f32_e32 v253, v253
	v_exp_f32_e32 v230, v230
	v_exp_f32_e32 v231, v231
	v_exp_f32_e32 v232, v232
	v_exp_f32_e32 v233, v233
	v_add_f32_e32 v250, 1.0, v250
	v_add_f32_e32 v251, 1.0, v251
	v_add_f32_e32 v252, 1.0, v252
	v_add_f32_e32 v253, 1.0, v253
	v_add_f32_e32 v230, 1.0, v230
	v_add_f32_e32 v231, 1.0, v231
	v_add_f32_e32 v232, 1.0, v232
	v_add_f32_e32 v233, 1.0, v233
	v_rcp_f32_e32 v250, v250
	v_rcp_f32_e32 v251, v251
	v_rcp_f32_e32 v252, v252
	v_rcp_f32_e32 v253, v253
	v_rcp_f32_e32 v230, v230
	v_rcp_f32_e32 v231, v231
	v_rcp_f32_e32 v232, v232
	v_rcp_f32_e32 v233, v233
	v_pk_mul_f32 v[54:55], v[220:221], v[54:55] op_sel_hi:[0,1]
	v_pk_mul_f32 v[56:57], v[220:221], v[56:57] op_sel_hi:[0,1]
	v_pk_mul_f32 v[50:51], v[220:221], v[50:51] op_sel_hi:[0,1]
	v_pk_mul_f32 v[52:53], v[220:221], v[52:53] op_sel_hi:[0,1]
	v_pk_mul_f32 v[54:55], v[250:251], v[54:55]
	v_pk_mul_f32 v[56:57], v[252:253], v[56:57]
	v_pk_mul_f32 v[50:51], v[230:231], v[50:51]
	v_pk_mul_f32 v[52:53], v[232:233], v[52:53]
	v_cvt_pk_bf16_f32 v62, v54, v55
	v_cvt_pk_bf16_f32 v63, v56, v57
	v_cvt_pk_bf16_f32 v64, v50, v51
	v_cvt_pk_bf16_f32 v65, v52, v53
	global_store_dwordx4 v[162:163], v[62:65], off
	v_fmamk_f32 v141, v153, 0x3a800000, v222
	v_rsq_f32_e32 v220, v141
	v_add_u32_e32 v184, 0x90, v140
	v_mad_i64_i32 v[162:163], vcc, v184, s10, v[224:225]
	v_pk_mul_f32 v[38:39], v[46:47], v[38:39]
	v_pk_mul_f32 v[40:41], v[48:49], v[40:41]
	v_pk_mul_f32 v[34:35], v[42:43], v[34:35]
	v_pk_mul_f32 v[36:37], v[44:45], v[36:37]
	v_mul_f32_e32 v142, 0xbfb8aa3b, v220
	v_mul_f32_e32 v220, v220, v220
	v_pk_mul_f32 v[250:251], v[142:143], v[46:47] op_sel_hi:[0,1]
	v_pk_mul_f32 v[252:253], v[142:143], v[48:49] op_sel_hi:[0,1]
	v_pk_mul_f32 v[230:231], v[142:143], v[42:43] op_sel_hi:[0,1]
	v_pk_mul_f32 v[232:233], v[142:143], v[44:45] op_sel_hi:[0,1]
	v_exp_f32_e32 v250, v250
	v_exp_f32_e32 v251, v251
	v_exp_f32_e32 v252, v252
	v_exp_f32_e32 v253, v253
	v_exp_f32_e32 v230, v230
	v_exp_f32_e32 v231, v231
; __device__ __forceinline__ unsigned cvtpk(float lo, float hi) { f32x2 v = {lo, hi}; bf16x2_t b = __builtin_convertvector(v, bf16x2_t); return __builtin_bit_cast(unsigned, b); }
;     __device__ __forceinline__ void operator()(const f32x4 (&acc)[2][2][4][2], const Unit& u, int wr, int wc, int fr, int fq, const float (&pv)[8]) const {
;     ...
;             for (int m = 0; m < 4; ++m) { const int row = row0 + ai * HALF + m * 16; const float rs = __builtin_amdgcn_rsqf(pv[ai * 4 + m] * (1.f / DM) + EPS);
;                 float hv[8];
; #pragma unroll
;                 for (int n = 0; n < 2; ++n)
; #pragma unroll
;                     for (int j = 0; j < 4; ++j) { const float g = acc[ai][0][m][n][j] * rs, uu = acc[ai][1][m][n][j] * rs;
;                         const float e = __builtin_amdgcn_exp2f(-g * LOG2E); hv[n * 4 + j] = g * uu * __builtin_amdgcn_rcpf(1.f + e); }
;                 u32x4 w; w.x = cvtpk(hv[0], hv[1]); w.y = cvtpk(hv[2], hv[3]); w.z = cvtpk(hv[4], hv[5]); w.w = cvtpk(hv[6], hv[7]);
;                 *(u32x4*)(H + (size_t)row * DFF + col0) = w; }
	v_exp_f32_e32 v232, v232
	v_exp_f32_e32 v233, v233
	v_add_f32_e32 v250, 1.0, v250
	v_add_f32_e32 v251, 1.0, v251
	v_add_f32_e32 v252, 1.0, v252
	v_add_f32_e32 v253, 1.0, v253
	v_add_f32_e32 v230, 1.0, v230
	v_add_f32_e32 v231, 1.0, v231
	v_add_f32_e32 v232, 1.0, v232
	v_add_f32_e32 v233, 1.0, v233
	v_rcp_f32_e32 v250, v250
	v_rcp_f32_e32 v251, v251
	v_rcp_f32_e32 v252, v252
	v_rcp_f32_e32 v253, v253
	v_rcp_f32_e32 v230, v230
	v_rcp_f32_e32 v231, v231
	v_rcp_f32_e32 v232, v232
	v_rcp_f32_e32 v233, v233
	v_pk_mul_f32 v[38:39], v[220:221], v[38:39] op_sel_hi:[0,1]
	v_pk_mul_f32 v[40:41], v[220:221], v[40:41] op_sel_hi:[0,1]
	v_pk_mul_f32 v[34:35], v[220:221], v[34:35] op_sel_hi:[0,1]
	v_pk_mul_f32 v[36:37], v[220:221], v[36:37] op_sel_hi:[0,1]
	v_pk_mul_f32 v[38:39], v[250:251], v[38:39]
	v_pk_mul_f32 v[40:41], v[252:253], v[40:41]
	v_pk_mul_f32 v[34:35], v[230:231], v[34:35]
	v_pk_mul_f32 v[36:37], v[232:233], v[36:37]
	v_cvt_pk_bf16_f32 v46, v38, v39
	v_cvt_pk_bf16_f32 v47, v40, v41
	v_cvt_pk_bf16_f32 v48, v34, v35
	v_cvt_pk_bf16_f32 v49, v36, v37
	global_store_dwordx4 v[162:163], v[46:49], off
	v_fmamk_f32 v141, v154, 0x3a800000, v222
	v_rsq_f32_e32 v220, v141
	v_add_u32_e32 v184, 0xa0, v140
	v_mad_i64_i32 v[162:163], vcc, v184, s10, v[224:225]
	v_pk_mul_f32 v[22:23], v[30:31], v[22:23]
	v_pk_mul_f32 v[24:25], v[32:33], v[24:25]
	v_pk_mul_f32 v[18:19], v[26:27], v[18:19]
	v_pk_mul_f32 v[20:21], v[28:29], v[20:21]
	v_mul_f32_e32 v142, 0xbfb8aa3b, v220
	v_mul_f32_e32 v220, v220, v220
	v_pk_mul_f32 v[250:251], v[142:143], v[30:31] op_sel_hi:[0,1]
	v_pk_mul_f32 v[252:253], v[142:143], v[32:33] op_sel_hi:[0,1]
	v_pk_mul_f32 v[230:231], v[142:143], v[26:27] op_sel_hi:[0,1]
	v_pk_mul_f32 v[232:233], v[142:143], v[28:29] op_sel_hi:[0,1]
	v_exp_f32_e32 v250, v250
	v_exp_f32_e32 v251, v251
	v_exp_f32_e32 v252, v252
	v_exp_f32_e32 v253, v253
	v_exp_f32_e32 v230, v230
	v_exp_f32_e32 v231, v231
	v_exp_f32_e32 v232, v232
	v_exp_f32_e32 v233, v233
	v_add_f32_e32 v250, 1.0, v250
	v_add_f32_e32 v251, 1.0, v251
	v_add_f32_e32 v252, 1.0, v252
	v_add_f32_e32 v253, 1.0, v253
	v_add_f32_e32 v230, 1.0, v230
	v_add_f32_e32 v231, 1.0, v231
	v_add_f32_e32 v232, 1.0, v232
	v_add_f32_e32 v233, 1.0, v233
	v_rcp_f32_e32 v250, v250
	v_rcp_f32_e32 v251, v251
	v_rcp_f32_e32 v252, v252
	v_rcp_f32_e32 v253, v253
	v_rcp_f32_e32 v230, v230
	v_rcp_f32_e32 v231, v231
	v_rcp_f32_e32 v232, v232
	v_rcp_f32_e32 v233, v233
	v_pk_mul_f32 v[22:23], v[220:221], v[22:23] op_sel_hi:[0,1]
	v_pk_mul_f32 v[24:25], v[220:221], v[24:25] op_sel_hi:[0,1]
	v_pk_mul_f32 v[18:19], v[220:221], v[18:19] op_sel_hi:[0,1]
	v_pk_mul_f32 v[20:21], v[220:221], v[20:21] op_sel_hi:[0,1]
	v_pk_mul_f32 v[22:23], v[250:251], v[22:23]
	v_pk_mul_f32 v[24:25], v[252:253], v[24:25]
	v_pk_mul_f32 v[18:19], v[230:231], v[18:19]
	v_pk_mul_f32 v[20:21], v[232:233], v[20:21]
	v_cvt_pk_bf16_f32 v30, v22, v23
	v_cvt_pk_bf16_f32 v31, v24, v25
	v_cvt_pk_bf16_f32 v32, v18, v19
	v_cvt_pk_bf16_f32 v33, v20, v21
	global_store_dwordx4 v[162:163], v[30:33], off
	v_fmamk_f32 v141, v155, 0x3a800000, v222
	v_rsq_f32_e32 v220, v141
	v_add_u32_e32 v184, 0xb0, v140
	v_mad_i64_i32 v[162:163], vcc, v184, s10, v[224:225]
	v_pk_mul_f32 v[6:7], v[14:15], v[6:7]
	v_pk_mul_f32 v[8:9], v[16:17], v[8:9]
	v_pk_mul_f32 v[2:3], v[10:11], v[2:3]
	v_pk_mul_f32 v[4:5], v[12:13], v[4:5]
	v_mul_f32_e32 v142, 0xbfb8aa3b, v220
	v_mul_f32_e32 v220, v220, v220
	v_pk_mul_f32 v[250:251], v[142:143], v[14:15] op_sel_hi:[0,1]
	v_pk_mul_f32 v[252:253], v[142:143], v[16:17] op_sel_hi:[0,1]
	v_pk_mul_f32 v[230:231], v[142:143], v[10:11] op_sel_hi:[0,1]
	v_pk_mul_f32 v[232:233], v[142:143], v[12:13] op_sel_hi:[0,1]
	v_exp_f32_e32 v250, v250
	v_exp_f32_e32 v251, v251
	v_exp_f32_e32 v252, v252
	v_exp_f32_e32 v253, v253
	v_exp_f32_e32 v230, v230
	v_exp_f32_e32 v231, v231
	v_exp_f32_e32 v232, v232
	v_exp_f32_e32 v233, v233
	v_add_f32_e32 v250, 1.0, v250
	v_add_f32_e32 v251, 1.0, v251
	v_add_f32_e32 v252, 1.0, v252
	v_add_f32_e32 v253, 1.0, v253
	v_add_f32_e32 v230, 1.0, v230
	v_add_f32_e32 v231, 1.0, v231
	v_add_f32_e32 v232, 1.0, v232
	v_add_f32_e32 v233, 1.0, v233
	v_rcp_f32_e32 v250, v250
	v_rcp_f32_e32 v251, v251
	v_rcp_f32_e32 v252, v252
	v_rcp_f32_e32 v253, v253
	v_rcp_f32_e32 v230, v230
	v_rcp_f32_e32 v231, v231
	v_rcp_f32_e32 v232, v232
	v_rcp_f32_e32 v233, v233
	v_pk_mul_f32 v[6:7], v[220:221], v[6:7] op_sel_hi:[0,1]
	v_pk_mul_f32 v[8:9], v[220:221], v[8:9] op_sel_hi:[0,1]
	v_pk_mul_f32 v[2:3], v[220:221], v[2:3] op_sel_hi:[0,1]
	v_pk_mul_f32 v[4:5], v[220:221], v[4:5] op_sel_hi:[0,1]
	v_pk_mul_f32 v[6:7], v[250:251], v[6:7]
	v_pk_mul_f32 v[8:9], v[252:253], v[8:9]
	v_pk_mul_f32 v[2:3], v[230:231], v[2:3]
	v_pk_mul_f32 v[4:5], v[232:233], v[4:5]
	v_cvt_pk_bf16_f32 v14, v6, v7
	v_cvt_pk_bf16_f32 v15, v8, v9
	v_cvt_pk_bf16_f32 v16, v2, v3
	v_cvt_pk_bf16_f32 v17, v4, v5
	global_store_dwordx4 v[162:163], v[14:17], off
	s_andn2_b64 vcc, exec, s[40:41]
	s_mov_b64 s[2:3], -1
	s_cbranch_vccnz .LBB0_142
	s_andn2_b64 vcc, exec, s[24:25]
	s_cbranch_vccnz .LBB0_141
	s_barrier
	s_branch .LBB0_141

; #define PG8_WAIT_V(n) asm volatile("s_waitcnt vmcnt(" #n ")" ::: "memory")
; #define PG8_BAR __builtin_amdgcn_s_barrier()
; template <class Epi>
; __device__ __forceinline__ void gemm_phase(LAS unsigned char* lds, const Gemm g, const StaticOrder& S, const Epi& E, const int wave_id) {
;     ...
;         if (wr == 0) PG8_BAR;
;         E(acc, cur, wr, wc, fr, fq, epre);
;         if (!has_next) break;
; #pragma unroll
;         for (int a = 0; a < 2; ++a)
; #pragma unroll
;             for (int b = 0; b < 2; ++b)
; #pragma unroll
;                 for (int m = 0; m < 4; ++m)
; #pragma unroll
;                     for (int n = 0; n < 2; ++n) acc[a][b][m][n] = (f32x4){0.f, 0.f, 0.f, 0.f};
;         cur = nxt; cA = nA; cB = nB; ++ui;
;         if (wr == 1) PG8_BAR;
;     }
;     PG8_WAIT_V(0);
;     PG8_BAR;
.LBB0_156:
	s_nop 0
	s_nop 0
	s_nop 0
	s_nop 0
	s_nop 0
	s_nop 0
	s_nop 0
	s_nop 0
	s_mov_b64 s[2:3], 0
